# HGRN2 scan: one workgroup barrier per chunk (stage-1 images and partial-output planes double-buffered by chunk parity), output store moved behind the barrier; scan load addresses from per-unit bases
# speedup vs baseline: 1.0041x; 1.0041x over previous
.LBB0_414:
	s_waitcnt lgkmcnt(0)
	s_barrier
	s_waitcnt vmcnt(15)
	v_add_u32_e32 v0, 0x9000, v62
	s_nop 8
	ds_read2_b32 v[2:3], v0 offset0:128 offset1:160
	v_add_u32_e32 v0, 0xa000, v62
	ds_read2_b32 v[4:5], v0 offset0:128 offset1:160
	v_add_u32_e32 v0, 0xb000, v62
	ds_read2_b32 v[6:7], v0 offset0:128 offset1:160
	v_add_u32_e32 v0, 0xc000, v62
	ds_read2_b32 v[8:9], v0 offset0:128 offset1:160
	s_waitcnt lgkmcnt(3)
	v_lshlrev_b32_e32 v10, 16, v2
	s_waitcnt lgkmcnt(2)
	v_lshlrev_b32_e32 v12, 16, v4
	s_waitcnt lgkmcnt(1)
	v_lshlrev_b32_e32 v14, 16, v6
	v_and_b32_e32 v11, 0xffff0000, v2
	s_waitcnt lgkmcnt(0)
	v_lshlrev_b32_e32 v16, 16, v8
	v_and_b32_e32 v13, 0xffff0000, v4
	v_and_b32_e32 v15, 0xffff0000, v6
	v_and_b32_e32 v17, 0xffff0000, v8
	v_lshlrev_b32_e32 v2, 16, v3
	v_lshlrev_b32_e32 v4, 16, v5
	v_lshlrev_b32_e32 v6, 16, v7
	v_lshlrev_b32_e32 v8, 16, v9
	v_and_b32_e32 v3, 0xffff0000, v3
	v_and_b32_e32 v5, 0xffff0000, v5
	v_and_b32_e32 v7, 0xffff0000, v7
	v_and_b32_e32 v9, 0xffff0000, v9
	v_pk_add_f32 v[2:3], v[2:3], v[4:5]
	v_pk_add_f32 v[4:5], v[6:7], v[8:9]
	v_pk_add_f32 v[10:11], v[10:11], v[12:13]
	v_pk_add_f32 v[12:13], v[14:15], v[16:17]
	v_pk_add_f32 v[2:3], v[2:3], v[4:5]
	v_pk_add_f32 v[10:11], v[10:11], v[12:13]
	v_cvt_pk_bf16_f32 v5, v2, v3
	v_add_co_u32_e32 v2, vcc, 0x7f0000, v38
	v_cvt_pk_bf16_f32 v4, v10, v11
	s_nop 0
	v_addc_co_u32_e32 v3, vcc, 0, v39, vcc
	global_store_dwordx2 v[2:3], v[4:5], off
	v_xor_b32_e32 v62, 0x10000, v62
	v_readlane_b32 s0, v254, 47
	s_waitcnt lgkmcnt(0)
	s_barrier
	s_add_i32 s37, s37, s96
	s_add_i32 s36, s36, s0
	s_cmpk_lt_i32 s37, 0x100
	s_cbranch_scc0 .LBB0_410

.LBB0_418:
	s_waitcnt lgkmcnt(0)
	s_barrier
	s_lshl_b64 s[6:7], s[8:9], 16
	v_add_u32_e32 v204, 0x9000, v62
	v_add_u32_e32 v206, 0xa000, v62
	v_add_u32_e32 v208, 0xb000, v62
	v_add_u32_e32 v210, 0xc000, v62
	ds_read2_b32 v[204:205], v204 offset0:128 offset1:160
	ds_read2_b32 v[206:207], v206 offset0:128 offset1:160
	ds_read2_b32 v[208:209], v208 offset0:128 offset1:160
	ds_read2_b32 v[210:211], v210 offset0:128 offset1:160
	ds_read_b64_tr_b16 v[104:105], v68 offset:8192
	ds_read_b64_tr_b16 v[106:107], v68 offset:8704
	ds_read_b64_tr_b16 v[108:109], v68
	ds_read_b64_tr_b16 v[110:111], v68 offset:512
	ds_read_b64_tr_b16 v[112:113], v68 offset:9216
	ds_read_b64_tr_b16 v[114:115], v68 offset:9728
	ds_read_b64_tr_b16 v[116:117], v68 offset:1024
	ds_read_b64_tr_b16 v[118:119], v68 offset:1536
	v_lshlrev_b32_e32 v192, 1, v52
	v_add3_u32 v103, s25, v64, v192
	v_add_u32_e32 v193, 0x6800, v103
	ds_read2_b64 v[120:123], v193 offset1:2
	ds_read2_b64 v[124:127], v193 offset0:4 offset1:6
	ds_read_b128 v[128:131], v71 offset:36864
	ds_read_b128 v[132:135], v71 offset:36896
	ds_read_b128 v[136:139], v71 offset:36928
	ds_read_b128 v[140:143], v71 offset:36960
	v_add_u32_e32 v194, v103, v65
	ds_read_b128 v[144:147], v66 offset:16384
	s_add_u32 s0, s0, 0x10000
	s_addc_u32 s1, s1, 0
	v_cvt_pk_bf16_f32 v184, v2, v3
	v_cvt_pk_bf16_f32 v185, v4, v5
	v_cvt_pk_bf16_f32 v186, v6, v7
	v_cvt_pk_bf16_f32 v187, v8, v9
	v_cvt_pk_bf16_f32 v188, v10, v11
	v_cvt_pk_bf16_f32 v189, v12, v13
	v_cvt_pk_bf16_f32 v190, v14, v15
	v_cvt_pk_bf16_f32 v191, v16, v17
	s_waitcnt lgkmcnt(11)
	v_mfma_f32_32x32x16_bf16 v[160:175], v[104:107], v[108:111], 0
	ds_read_b128 v[148:151], v66 offset:16416
	ds_read_b128 v[152:155], v194 offset:26624
	ds_read_b128 v[156:159], v194 offset:26656
	s_mov_b32 s8, s24
	s_waitcnt lgkmcnt(10)
	v_mfma_f32_32x32x16_bf16 v[160:175], v[112:115], v[116:119], v[160:175]
	s_waitcnt lgkmcnt(4)
	v_pk_mul_f32 v[2:3], v[2:3], v[128:129]
	v_pk_mul_f32 v[4:5], v[4:5], v[130:131]
	v_pk_mul_f32 v[6:7], v[6:7], v[132:133]
	v_pk_mul_f32 v[8:9], v[8:9], v[134:135]
	v_pk_mul_f32 v[10:11], v[10:11], v[136:137]
	v_pk_mul_f32 v[12:13], v[12:13], v[138:139]
	v_pk_mul_f32 v[14:15], v[14:15], v[140:141]
	v_pk_mul_f32 v[16:17], v[16:17], v[142:143]
	v_lshlrev_b32_e32 v212, 16, v204
	v_lshlrev_b32_e32 v214, 16, v206
	v_lshlrev_b32_e32 v216, 16, v208
	v_lshlrev_b32_e32 v218, 16, v210
	v_and_b32_e32 v213, 0xffff0000, v204
	v_and_b32_e32 v215, 0xffff0000, v206
	v_and_b32_e32 v217, 0xffff0000, v208
	v_and_b32_e32 v219, 0xffff0000, v210
	v_lshlrev_b32_e32 v204, 16, v205
	v_lshlrev_b32_e32 v206, 16, v207
	v_lshlrev_b32_e32 v208, 16, v209
	v_lshlrev_b32_e32 v210, 16, v211
	v_and_b32_e32 v205, 0xffff0000, v205
	v_and_b32_e32 v207, 0xffff0000, v207
	v_and_b32_e32 v209, 0xffff0000, v209
	v_and_b32_e32 v211, 0xffff0000, v211
	v_pk_add_f32 v[212:213], v[212:213], v[214:215]
	v_pk_add_f32 v[214:215], v[216:217], v[218:219]
	v_pk_add_f32 v[204:205], v[204:205], v[206:207]
	v_pk_add_f32 v[206:207], v[208:209], v[210:211]
	v_pk_add_f32 v[212:213], v[212:213], v[214:215]
	v_pk_add_f32 v[204:205], v[204:205], v[206:207]
	v_cvt_pk_bf16_f32 v206, v212, v213
	v_cvt_pk_bf16_f32 v207, v204, v205
	v_lshl_add_u64 v[204:205], v[38:39], 0, s[6:7]
	s_cmp_eq_u32 s0, 0x10000
	s_cbranch_scc1 .Lscan_nostore
	global_store_dwordx2 v[204:205], v[206:207], off
	v_xor_b32_e32 v62, 0x10000, v62
.Lscan_nostore:
	v_cndmask_b32_e64 v195, v160, 0, s[46:47]
	v_cndmask_b32_e64 v160, v195, v160, s[48:49]
	v_cndmask_b32_e64 v161, 0, v161, s[48:49]
	v_cndmask_b32_e64 v162, v162, 0, s[50:51]
	v_cndmask_b32_e64 v163, v163, 0, s[52:53]
	v_cndmask_b32_e64 v164, v164, 0, s[54:55]
	v_cndmask_b32_e64 v165, v165, 0, s[56:57]
	v_cndmask_b32_e64 v166, v166, 0, s[58:59]
	v_cndmask_b32_e64 v167, v167, 0, s[60:61]
	v_cndmask_b32_e64 v168, v168, 0, s[62:63]
	v_cndmask_b32_e64 v169, v169, 0, s[64:65]
	v_cndmask_b32_e64 v170, v170, 0, s[66:67]
	v_cndmask_b32_e64 v171, v171, 0, s[68:69]
	v_cndmask_b32_e64 v172, v172, 0, s[70:71]
	v_cndmask_b32_e64 v173, v173, 0, s[72:73]
	v_cndmask_b32_e64 v174, v174, 0, s[74:75]
	v_cndmask_b32_e64 v175, v175, 0, s[76:77]
	v_cvt_pk_bf16_f32 v176, v160, v161
	v_cvt_pk_bf16_f32 v177, v162, v163
	v_cvt_pk_bf16_f32 v178, v164, v165
	v_cvt_pk_bf16_f32 v179, v166, v167
	v_cvt_pk_bf16_f32 v180, v168, v169
	v_cvt_pk_bf16_f32 v181, v170, v171
	v_cvt_pk_bf16_f32 v182, v172, v173
	v_cvt_pk_bf16_f32 v183, v174, v175
	v_mfma_f32_32x32x16_bf16 v[18:33], v[120:123], v[176:179], 0
	v_mfma_f32_32x32x16_bf16 v[18:33], v[184:187], v[108:111], v[18:33]
	v_mfma_f32_32x32x16_bf16 v[18:33], v[124:127], v[180:183], v[18:33]
	v_mfma_f32_32x32x16_bf16 v[18:33], v[188:191], v[116:119], v[18:33]
	s_waitcnt lgkmcnt(1)
	v_mfma_f32_32x32x16_bf16 v[2:17], v[144:147], v[152:155], v[2:17]
	s_waitcnt lgkmcnt(0)
	v_mfma_f32_32x32x16_bf16 v[2:17], v[148:151], v[156:159], v[2:17]
	s_nop 7
	v_cvt_pk_bf16_f32 v18, v18, v19
	ds_write_b32 v75, v18 offset:37376
	v_cvt_pk_bf16_f32 v18, v20, v21
	ds_write_b32 v76, v18 offset:37376
	v_cvt_pk_bf16_f32 v18, v22, v23
	ds_write_b32 v77, v18 offset:37376
	v_cvt_pk_bf16_f32 v18, v24, v25
	ds_write_b32 v78, v18 offset:37376
	v_cvt_pk_bf16_f32 v18, v26, v27
	ds_write_b32 v79, v18 offset:37376
	v_cvt_pk_bf16_f32 v18, v28, v29
	ds_write_b32 v80, v18 offset:37376
	v_cvt_pk_bf16_f32 v18, v30, v31
	ds_write_b32 v81, v18 offset:37376
	v_cvt_pk_bf16_f32 v18, v32, v33
	ds_write_b32 v82, v18 offset:37376
	v_xor_b32_e32 v68, 0x10000, v68
	v_xor_b32_e32 v71, 0x10000, v71
	v_xor_b32_e32 v66, 0x10000, v66
	v_xor_b32_e32 v75, 0x10000, v75
	v_xor_b32_e32 v76, 0x10000, v76
	v_xor_b32_e32 v77, 0x10000, v77
	v_xor_b32_e32 v78, 0x10000, v78
	v_xor_b32_e32 v79, 0x10000, v79
	v_xor_b32_e32 v80, 0x10000, v80
	v_xor_b32_e32 v81, 0x10000, v81
	v_xor_b32_e32 v82, 0x10000, v82
	s_cmp_lg_u32 s0, 0x800000
	s_cbranch_scc0 .LBB0_414
.LBB0_419:
	s_waitcnt vmcnt(14)
	v_cvt_f32_f16_e32 v18, v53
	s_waitcnt vmcnt(13)
	v_cvt_f32_f16_e32 v19, v54
	s_waitcnt vmcnt(11)
	v_cvt_f32_f16_e32 v22, v59
	s_waitcnt vmcnt(6)
	v_cvt_f32_f16_e32 v24, v69
	v_add_f32_e32 v21, 0, v18
	v_mul_f32_e32 v18, 0x3fb8aa3b, v18
	v_exp_f32_e32 v20, v18
	v_add_f32_e32 v18, v21, v19
	v_mul_f32_e32 v19, 0x3fb8aa3b, v19
	v_exp_f32_e32 v21, v19
	v_cvt_f32_f16_e32 v19, v63
	v_add_f32_e32 v18, v18, v22
	s_waitcnt vmcnt(3)
	v_cvt_f32_f16_e32 v26, v72
	v_mul_f32_e32 v22, 0x3fb8aa3b, v22
	v_add_f32_e32 v18, v18, v19
	v_mul_f32_e32 v19, 0x3fb8aa3b, v19
	v_exp_f32_e32 v23, v19
	v_cvt_f32_f16_e32 v19, v70
	v_add_f32_e32 v18, v18, v24
	v_exp_f32_e32 v22, v22
	v_mul_f32_e32 v24, 0x3fb8aa3b, v24
	v_add_f32_e32 v18, v18, v19
	v_mul_f32_e32 v19, 0x3fb8aa3b, v19
	v_exp_f32_e32 v25, v19
	s_waitcnt vmcnt(2)
	v_cvt_f32_f16_e32 v19, v73
	v_add_f32_e32 v18, v18, v26
	v_exp_f32_e32 v24, v24
	v_mul_f32_e32 v26, 0x3fb8aa3b, v26
	v_add_f32_e32 v29, v18, v19
	v_mul_f32_e32 v19, 0x3fb8aa3b, v19
	ds_bpermute_b32 v18, v55, v29
	ds_bpermute_b32 v28, v56, v29
	v_exp_f32_e32 v27, v19
	ds_bpermute_b32 v19, v57, v29
	ds_bpermute_b32 v29, v58, v29
	s_waitcnt lgkmcnt(3)
	v_cndmask_b32_e64 v30, v18, 0, s[40:41]
	s_waitcnt lgkmcnt(2)
	v_cndmask_b32_e64 v31, 0, v28, s[42:43]
	v_add_f32_e32 v30, v30, v31
	s_waitcnt lgkmcnt(1)
	v_cndmask_b32_e64 v31, 0, v19, s[44:45]
	v_add_f32_e32 v30, v30, v31
	s_waitcnt lgkmcnt(0)
	v_pk_add_f32 v[18:19], v[18:19], v[28:29]
	v_lshlrev_b32_e32 v29, 16, v41
	v_add_f32_e32 v18, v18, v19
	v_mul_f32_e32 v19, 0x3fb8aa3b, v30
	v_exp_f32_e32 v19, v19
	v_mul_f32_e32 v18, 0x3fb8aa3b, v18
	v_lshlrev_b32_e32 v28, 16, v0
	v_exp_f32_e32 v18, v18
	v_mul_f32_e32 v30, v20, v19
	v_mul_f32_e32 v31, v21, v30
	v_rcp_f32_e32 v32, v30
	v_rcp_f32_e32 v33, v31
	v_pk_mul_f32 v[28:29], v[30:31], v[28:29]
	v_mul_f32_e32 v30, v22, v31
	v_mul_f32_e32 v31, v23, v30
	v_rcp_f32_e32 v86, v30
	v_rcp_f32_e32 v87, v31
	v_pk_add_f32 v[20:21], v[20:21], 1.0 op_sel_hi:[1,0] neg_lo:[1,0] neg_hi:[1,0]
	v_pk_mul_f32 v[84:85], v[18:19], v[32:33] op_sel_hi:[0,1]
	v_exp_f32_e32 v26, v26
	v_pk_mul_f32 v[84:85], v[20:21], v[84:85]
	v_pk_mul_f32 v[32:33], v[20:21], v[32:33]
	v_lshlrev_b32_e32 v21, 16, v43
	v_lshlrev_b32_e32 v20, 16, v40
	v_pk_mul_f32 v[88:89], v[30:31], v[20:21]
	v_pk_add_f32 v[20:21], v[22:23], 1.0 op_sel_hi:[1,0] neg_lo:[1,0] neg_hi:[1,0]
	v_pk_mul_f32 v[22:23], v[18:19], v[86:87] op_sel_hi:[0,1]
	v_pk_mul_f32 v[90:91], v[20:21], v[22:23]
	v_mul_f32_e32 v22, v24, v31
	v_pk_mul_f32 v[86:87], v[20:21], v[86:87]
	s_waitcnt vmcnt(0)
	v_lshlrev_b32_e32 v21, 16, v45
	v_mul_f32_e32 v23, v25, v22
	v_lshlrev_b32_e32 v20, 16, v42
	v_rcp_f32_e32 v30, v22
	v_rcp_f32_e32 v31, v23
	v_pk_mul_f32 v[92:93], v[22:23], v[20:21]
	v_mul_f32_e32 v22, v26, v23
	v_mul_f32_e32 v23, v27, v22
	v_rcp_f32_e32 v94, v22
	v_rcp_f32_e32 v95, v23
	v_pk_add_f32 v[20:21], v[24:25], 1.0 op_sel_hi:[1,0] neg_lo:[1,0] neg_hi:[1,0]
	v_pk_mul_f32 v[24:25], v[18:19], v[30:31] op_sel_hi:[0,1]
	v_pk_mul_f32 v[24:25], v[20:21], v[24:25]
	v_pk_mul_f32 v[30:31], v[20:21], v[30:31]
	v_lshlrev_b32_e32 v21, 16, v49
	v_lshlrev_b32_e32 v20, 16, v44
	v_pk_mul_f32 v[96:97], v[22:23], v[20:21]
	v_pk_add_f32 v[20:21], v[26:27], 1.0 op_sel_hi:[1,0] neg_lo:[1,0] neg_hi:[1,0]
	v_pk_mul_f32 v[22:23], v[18:19], v[94:95] op_sel_hi:[0,1]
	v_pk_mul_f32 v[26:27], v[20:21], v[22:23]
	v_pk_mul_f32 v[94:95], v[20:21], v[94:95]
	v_cvt_pk_bf16_f32 v20, v28, v29
	v_cvt_pk_bf16_f32 v21, v88, v89
	v_cvt_pk_bf16_f32 v22, v92, v93
	v_cvt_pk_bf16_f32 v23, v96, v97
	ds_write_b128 v60, v[20:23]
	v_cvt_pk_bf16_f32 v20, v32, v33
	v_cvt_pk_bf16_f32 v21, v86, v87
	v_cvt_pk_bf16_f32 v22, v30, v31
	v_cvt_pk_bf16_f32 v23, v94, v95
	ds_write_b128 v60, v[20:23] offset:8192
	v_cvt_pk_bf16_f32 v20, v84, v85
	v_cvt_pk_bf16_f32 v21, v90, v91
	v_cvt_pk_bf16_f32 v22, v24, v25
	v_cvt_pk_bf16_f32 v23, v26, v27
	ds_write_b128 v61, v[20:23] offset:16384
	s_and_saveexec_b64 vcc, s[40:41]
	ds_write_b32 v74, v18 offset:36864
	s_or_b64 exec, exec, vcc
	v_xor_b32_e32 v60, 0x10000, v60
	v_xor_b32_e32 v61, 0x10000, v61
	v_xor_b32_e32 v74, 0x10000, v74
	s_add_i32 s24, s8, 1
	s_bitcmp1_b32 s24, 0
	s_cselect_b32 s6, 0x1400, 0
	s_add_i32 s25, s6, 0
	s_and_saveexec_b64 vcc, s[38:39]
	s_cbranch_execnz .LBB0_424
	s_or_b64 exec, exec, vcc
	s_cmp_eq_u32 s0, 0x7f0000
	s_cbranch_scc0 .LBB0_425
.LBB0_423:
	s_branch .LBB0_418
.LBB0_424:
	v_lshlrev_b32_e32 v18, 1, v48
	v_add3_u32 v18, s25, v67, v18
	ds_write_b16 v18, v34 offset:26624
	ds_write_b16_d16_hi v18, v34 offset:26704
	ds_write_b16 v18, v35 offset:26784
	ds_write_b16_d16_hi v18, v35 offset:26864
	ds_write_b16 v18, v36 offset:26944
	ds_write_b16_d16_hi v18, v36 offset:27024
	ds_write_b16 v18, v37 offset:27104
	ds_write_b16_d16_hi v18, v37 offset:27184
	s_or_b64 exec, exec, vcc
	s_cmp_eq_u32 s0, 0x7f0000
	s_cbranch_scc1 .LBB0_423

.LBB0_427:
	s_or_b64 exec, exec, vcc
	s_branch .LBB0_418
